# GEMM tile headers: accumulators zeroed with 64-bit moves (63 instead of 126 VALU per tile)
# baseline (speedup 1.0000x reference)
.LBB0_396:
	s_ashr_i32 s65, s64, 31
	s_lshl_b64 s[10:11], s[64:65], 19
	s_add_u32 s10, s1, s10
	s_addc_u32 s11, s4, s11
	s_and_b64 s[12:13], s[40:41], exec
	s_cselect_b32 s23, s11, s85
	s_cselect_b32 s26, s10, s84
	s_ashr_i32 s45, s44, 31
	s_lshl_b64 s[12:13], s[44:45], 19
	s_add_u32 s12, s5, s12
	s_addc_u32 s13, s30, s13
	s_and_b64 s[28:29], s[40:41], exec
	s_cselect_b32 s27, s13, s43
	s_cselect_b32 s28, s12, s42
	s_add_u32 s24, s84, 0x40080
	s_addc_u32 s25, s85, 0
	s_add_u32 s29, s42, 0x100
	v_mov_b32_e32 v0, 0
	s_addc_u32 s45, s43, 0
	s_mov_b32 s65, -2
	v_mov_b32_e32 v1, v0
	v_mov_b64_e32 v[2:3], 0
	v_mov_b64_e32 v[4:5], 0
	v_mov_b64_e32 v[6:7], 0
	v_mov_b64_e32 v[16:17], 0
	v_mov_b64_e32 v[18:19], 0
	v_mov_b64_e32 v[20:21], 0
	v_mov_b64_e32 v[22:23], 0
	v_mov_b64_e32 v[32:33], 0
	v_mov_b64_e32 v[34:35], 0
	v_mov_b64_e32 v[36:37], 0
	v_mov_b64_e32 v[38:39], 0
	v_mov_b64_e32 v[48:49], 0
	v_mov_b64_e32 v[50:51], 0
	v_mov_b64_e32 v[52:53], 0
	v_mov_b64_e32 v[54:55], 0
	v_mov_b64_e32 v[8:9], 0
	v_mov_b64_e32 v[10:11], 0
	v_mov_b64_e32 v[12:13], 0
	v_mov_b64_e32 v[14:15], 0
	v_mov_b64_e32 v[24:25], 0
	v_mov_b64_e32 v[26:27], 0
	v_mov_b64_e32 v[28:29], 0
	v_mov_b64_e32 v[30:31], 0
	v_mov_b64_e32 v[40:41], 0
	v_mov_b64_e32 v[42:43], 0
	v_mov_b64_e32 v[44:45], 0
	v_mov_b64_e32 v[46:47], 0
	v_mov_b64_e32 v[56:57], 0
	v_mov_b64_e32 v[58:59], 0
	v_mov_b64_e32 v[60:61], 0
	v_mov_b64_e32 v[62:63], 0
	v_mov_b64_e32 v[80:81], 0
	v_mov_b64_e32 v[82:83], 0
	v_mov_b64_e32 v[84:85], 0
	v_mov_b64_e32 v[86:87], 0
	v_mov_b64_e32 v[96:97], 0
	v_mov_b64_e32 v[98:99], 0
	v_mov_b64_e32 v[100:101], 0
	v_mov_b64_e32 v[102:103], 0
	v_mov_b64_e32 v[112:113], 0
	v_mov_b64_e32 v[114:115], 0
	v_mov_b64_e32 v[116:117], 0
	v_mov_b64_e32 v[118:119], 0
	v_mov_b64_e32 v[128:129], 0
	v_mov_b64_e32 v[130:131], 0
	v_mov_b64_e32 v[132:133], 0
	v_mov_b64_e32 v[134:135], 0
	v_mov_b64_e32 v[88:89], 0
	v_mov_b64_e32 v[90:91], 0
	v_mov_b64_e32 v[92:93], 0
	v_mov_b64_e32 v[94:95], 0
	v_mov_b64_e32 v[104:105], 0
	v_mov_b64_e32 v[106:107], 0
	v_mov_b64_e32 v[108:109], 0
	v_mov_b64_e32 v[110:111], 0
	v_mov_b64_e32 v[120:121], 0
	v_mov_b64_e32 v[122:123], 0
	v_mov_b64_e32 v[124:125], 0
	v_mov_b64_e32 v[126:127], 0
	v_mov_b64_e32 v[136:137], 0
	v_mov_b64_e32 v[138:139], 0
	v_mov_b64_e32 v[140:141], 0
	v_mov_b64_e32 v[142:143], 0

.LBB0_558:
	s_ashr_i32 s19, s18, 31
	s_lshl_b64 s[20:21], s[18:19], 19
	s_add_u32 s20, s4, s20
	s_addc_u32 s21, s5, s21
	s_and_b64 s[40:41], s[38:39], exec
	s_cselect_b32 s19, s21, s45
	s_cselect_b32 s23, s20, s44
	s_ashr_i32 s15, s14, 31
	s_lshl_b64 s[40:41], s[14:15], 19
	s_add_u32 s40, s17, s40
	s_addc_u32 s41, s26, s41
	s_and_b64 s[60:61], s[38:39], exec
	s_cselect_b32 s15, s41, s65
	s_cselect_b32 s43, s40, s64
	s_add_u32 s44, s44, 0x40080
	s_addc_u32 s45, s45, 0
	s_add_u32 s60, s64, 0x100
	v_mov_b32_e32 v0, 0
	s_addc_u32 s61, s65, 0
	s_mov_b32 s62, -2
	v_mov_b32_e32 v1, v0
	v_mov_b64_e32 v[2:3], 0
	v_mov_b64_e32 v[4:5], 0
	v_mov_b64_e32 v[6:7], 0
	v_mov_b64_e32 v[16:17], 0
	v_mov_b64_e32 v[18:19], 0
	v_mov_b64_e32 v[20:21], 0
	v_mov_b64_e32 v[22:23], 0
	v_mov_b64_e32 v[32:33], 0
	v_mov_b64_e32 v[34:35], 0
	v_mov_b64_e32 v[36:37], 0
	v_mov_b64_e32 v[38:39], 0
	v_mov_b64_e32 v[48:49], 0
	v_mov_b64_e32 v[50:51], 0
	v_mov_b64_e32 v[52:53], 0
	v_mov_b64_e32 v[54:55], 0
	v_mov_b64_e32 v[8:9], 0
	v_mov_b64_e32 v[10:11], 0
	v_mov_b64_e32 v[12:13], 0
	v_mov_b64_e32 v[14:15], 0
	v_mov_b64_e32 v[24:25], 0
	v_mov_b64_e32 v[26:27], 0
	v_mov_b64_e32 v[28:29], 0
	v_mov_b64_e32 v[30:31], 0
	v_mov_b64_e32 v[40:41], 0
	v_mov_b64_e32 v[42:43], 0
	v_mov_b64_e32 v[44:45], 0
	v_mov_b64_e32 v[46:47], 0
	v_mov_b64_e32 v[56:57], 0
	v_mov_b64_e32 v[58:59], 0
	v_mov_b64_e32 v[60:61], 0
	v_mov_b64_e32 v[62:63], 0
	v_mov_b64_e32 v[64:65], 0
	v_mov_b64_e32 v[66:67], 0
	v_mov_b64_e32 v[68:69], 0
	v_mov_b64_e32 v[70:71], 0
	v_mov_b64_e32 v[80:81], 0
	v_mov_b64_e32 v[82:83], 0
	v_mov_b64_e32 v[84:85], 0
	v_mov_b64_e32 v[86:87], 0
	v_mov_b64_e32 v[96:97], 0
	v_mov_b64_e32 v[98:99], 0
	v_mov_b64_e32 v[100:101], 0
	v_mov_b64_e32 v[102:103], 0
	v_mov_b64_e32 v[128:129], 0
	v_mov_b64_e32 v[130:131], 0
	v_mov_b64_e32 v[132:133], 0
	v_mov_b64_e32 v[134:135], 0
	v_mov_b64_e32 v[72:73], 0
	v_mov_b64_e32 v[74:75], 0
	v_mov_b64_e32 v[76:77], 0
	v_mov_b64_e32 v[78:79], 0
	v_mov_b64_e32 v[88:89], 0
	v_mov_b64_e32 v[90:91], 0
	v_mov_b64_e32 v[92:93], 0
	v_mov_b64_e32 v[94:95], 0
	v_mov_b64_e32 v[104:105], 0
	v_mov_b64_e32 v[106:107], 0
	v_mov_b64_e32 v[108:109], 0
	v_mov_b64_e32 v[110:111], 0
	v_mov_b64_e32 v[136:137], 0
	v_mov_b64_e32 v[138:139], 0
	v_mov_b64_e32 v[140:141], 0
	v_mov_b64_e32 v[142:143], 0

.LBB0_634:
	s_ashr_i32 s19, s18, 31
	s_lshl_b64 s[14:15], s[18:19], 21
	s_add_u32 s64, s36, s14
	s_addc_u32 s65, s37, s15
	s_and_b64 s[14:15], s[40:41], exec
	s_cselect_b32 s19, s65, s11
	s_cselect_b32 s22, s64, s10
	s_ashr_i32 s17, s16, 31
	s_lshl_b64 s[14:15], s[16:17], 21
	s_add_u32 s14, s63, s14
	s_addc_u32 s15, s61, s15
	s_and_b64 s[20:21], s[40:41], exec
	s_cselect_b32 s17, s15, s13
	s_cselect_b32 s23, s14, s12
	s_add_u32 s10, s10, 0x100080
	s_addc_u32 s11, s11, 0
	s_add_u32 s24, s12, 0x100
	v_mov_b32_e32 v0, 0
	s_addc_u32 s25, s13, 0
	s_mov_b32 s26, -2
	s_waitcnt lgkmcnt(0)
	v_mov_b32_e32 v1, v0
	v_mov_b64_e32 v[2:3], 0
	v_mov_b64_e32 v[4:5], 0
	v_mov_b64_e32 v[6:7], 0
	v_mov_b64_e32 v[8:9], 0
	v_mov_b64_e32 v[10:11], 0
	v_mov_b64_e32 v[12:13], 0
	v_mov_b64_e32 v[14:15], 0
	v_mov_b64_e32 v[16:17], 0
	v_mov_b64_e32 v[18:19], 0
	v_mov_b64_e32 v[20:21], 0
	v_mov_b64_e32 v[22:23], 0
	v_mov_b64_e32 v[24:25], 0
	v_mov_b64_e32 v[26:27], 0
	v_mov_b64_e32 v[28:29], 0
	v_mov_b64_e32 v[30:31], 0
	v_mov_b64_e32 v[64:65], 0
	v_mov_b64_e32 v[66:67], 0
	v_mov_b64_e32 v[68:69], 0
	v_mov_b64_e32 v[70:71], 0
	v_mov_b64_e32 v[72:73], 0
	v_mov_b64_e32 v[74:75], 0
	v_mov_b64_e32 v[76:77], 0
	v_mov_b64_e32 v[78:79], 0
	v_mov_b64_e32 v[80:81], 0
	v_mov_b64_e32 v[82:83], 0
	v_mov_b64_e32 v[84:85], 0
	v_mov_b64_e32 v[86:87], 0
	v_mov_b64_e32 v[104:105], 0
	v_mov_b64_e32 v[106:107], 0
	v_mov_b64_e32 v[108:109], 0
	v_mov_b64_e32 v[110:111], 0
	v_mov_b64_e32 v[32:33], 0
	v_mov_b64_e32 v[34:35], 0
	v_mov_b64_e32 v[36:37], 0
	v_mov_b64_e32 v[38:39], 0
	v_mov_b64_e32 v[40:41], 0
	v_mov_b64_e32 v[42:43], 0
	v_mov_b64_e32 v[44:45], 0
	v_mov_b64_e32 v[46:47], 0
	v_mov_b64_e32 v[48:49], 0
	v_mov_b64_e32 v[50:51], 0
	v_mov_b64_e32 v[52:53], 0
	v_mov_b64_e32 v[54:55], 0
	v_mov_b64_e32 v[56:57], 0
	v_mov_b64_e32 v[58:59], 0
	v_mov_b64_e32 v[60:61], 0
	v_mov_b64_e32 v[62:63], 0
	v_mov_b64_e32 v[112:113], 0
	v_mov_b64_e32 v[114:115], 0
	v_mov_b64_e32 v[116:117], 0
	v_mov_b64_e32 v[118:119], 0
	v_mov_b64_e32 v[120:121], 0
	v_mov_b64_e32 v[122:123], 0
	v_mov_b64_e32 v[124:125], 0
	v_mov_b64_e32 v[126:127], 0
	v_mov_b64_e32 v[128:129], 0
	v_mov_b64_e32 v[130:131], 0
	v_mov_b64_e32 v[132:133], 0
	v_mov_b64_e32 v[134:135], 0
	v_mov_b64_e32 v[136:137], 0
	v_mov_b64_e32 v[138:139], 0
	v_mov_b64_e32 v[140:141], 0
	v_mov_b64_e32 v[142:143], 0

.LBB0_789:
	s_ashr_i32 s63, s62, 31
	s_lshl_b64 s[64:65], s[62:63], 19
	s_add_u32 s64, s0, s64
	s_addc_u32 s65, s1, s65
	s_and_b64 s[66:67], s[38:39], exec
	s_cselect_b32 s63, s65, s29
	s_cselect_b32 s73, s64, s28
	s_ashr_i32 s45, s44, 31
	s_lshl_b64 s[66:67], s[44:45], 19
	s_add_u32 s66, s4, s66
	s_addc_u32 s67, s5, s67
	s_and_b64 s[68:69], s[38:39], exec
	s_cselect_b32 s45, s67, s31
	s_cselect_b32 s74, s66, s30
	s_add_u32 s28, s28, 0x40080
	s_addc_u32 s29, s29, 0
	s_add_u32 s75, s30, 0x100
	v_mov_b32_e32 v0, 0
	s_addc_u32 s76, s31, 0
	s_mov_b32 s77, -2
	v_mov_b32_e32 v1, v0
	v_mov_b64_e32 v[2:3], 0
	v_mov_b64_e32 v[4:5], 0
	v_mov_b64_e32 v[6:7], 0
	v_mov_b64_e32 v[16:17], 0
	v_mov_b64_e32 v[18:19], 0
	v_mov_b64_e32 v[20:21], 0
	v_mov_b64_e32 v[22:23], 0
	v_mov_b64_e32 v[32:33], 0
	v_mov_b64_e32 v[34:35], 0
	v_mov_b64_e32 v[36:37], 0
	v_mov_b64_e32 v[38:39], 0
	v_mov_b64_e32 v[48:49], 0
	v_mov_b64_e32 v[50:51], 0
	v_mov_b64_e32 v[52:53], 0
	v_mov_b64_e32 v[54:55], 0
	v_mov_b64_e32 v[8:9], 0
	v_mov_b64_e32 v[10:11], 0
	v_mov_b64_e32 v[12:13], 0
	v_mov_b64_e32 v[14:15], 0
	v_mov_b64_e32 v[24:25], 0
	v_mov_b64_e32 v[26:27], 0
	v_mov_b64_e32 v[28:29], 0
	v_mov_b64_e32 v[30:31], 0
	v_mov_b64_e32 v[40:41], 0
	v_mov_b64_e32 v[42:43], 0
	v_mov_b64_e32 v[44:45], 0
	v_mov_b64_e32 v[46:47], 0
	v_mov_b64_e32 v[56:57], 0
	v_mov_b64_e32 v[58:59], 0
	v_mov_b64_e32 v[60:61], 0
	v_mov_b64_e32 v[62:63], 0
	v_mov_b64_e32 v[66:67], 0
	v_mov_b64_e32 v[68:69], 0
	v_mov_b64_e32 v[70:71], 0
	v_mov_b64_e32 v[72:73], 0
	v_mov_b64_e32 v[82:83], 0
	v_mov_b64_e32 v[84:85], 0
	v_mov_b64_e32 v[86:87], 0
	v_mov_b64_e32 v[88:89], 0
	v_mov_b64_e32 v[98:99], 0
	v_mov_b64_e32 v[100:101], 0
	v_mov_b64_e32 v[106:107], 0
	v_mov_b64_e32 v[108:109], 0
	v_mov_b64_e32 v[130:131], 0
	s_waitcnt vmcnt(0)
	v_mov_b64_e32 v[132:133], 0
	v_mov_b64_e32 v[134:135], 0
	v_mov_b64_e32 v[136:137], 0
	v_mov_b64_e32 v[74:75], 0
	v_mov_b64_e32 v[76:77], 0
	v_mov_b64_e32 v[78:79], 0
	v_mov_b64_e32 v[80:81], 0
	v_mov_b64_e32 v[90:91], 0
	v_mov_b64_e32 v[92:93], 0
	v_mov_b64_e32 v[94:95], 0
	v_mov_b64_e32 v[96:97], 0
	v_mov_b64_e32 v[122:123], 0
	v_mov_b64_e32 v[124:125], 0
	v_mov_b64_e32 v[126:127], 0
	v_mov_b64_e32 v[128:129], 0
	v_mov_b64_e32 v[138:139], 0
	v_mov_b64_e32 v[140:141], 0
	v_mov_b64_e32 v[142:143], 0
	v_mov_b64_e32 v[144:145], 0

.LBB0_892:
	s_ashr_i32 s63, s62, 31
	s_lshl_b64 s[64:65], s[62:63], 19
	s_add_u32 s64, s0, s64
	s_addc_u32 s65, s1, s65
	s_and_b64 s[66:67], s[38:39], exec
	s_cselect_b32 s63, s65, s29
	s_cselect_b32 s75, s64, s28
	s_ashr_i32 s45, s44, 31
	s_lshl_b64 s[66:67], s[44:45], 19
	s_add_u32 s66, s4, s66
	s_addc_u32 s67, s5, s67
	s_and_b64 s[68:69], s[38:39], exec
	s_cselect_b32 s45, s67, s31
	s_cselect_b32 s76, s66, s30
	s_add_u32 s28, s28, 0x40080
	s_addc_u32 s29, s29, 0
	s_add_u32 s77, s30, 0x100
	v_mov_b32_e32 v0, 0
	s_addc_u32 s82, s31, 0
	s_mov_b32 s83, -2
	v_mov_b32_e32 v1, v0
	v_mov_b64_e32 v[2:3], 0
	v_mov_b64_e32 v[4:5], 0
	v_mov_b64_e32 v[6:7], 0
	v_mov_b64_e32 v[16:17], 0
	v_mov_b64_e32 v[18:19], 0
	v_mov_b64_e32 v[20:21], 0
	v_mov_b64_e32 v[22:23], 0
	v_mov_b64_e32 v[32:33], 0
	v_mov_b64_e32 v[34:35], 0
	v_mov_b64_e32 v[36:37], 0
	v_mov_b64_e32 v[38:39], 0
	v_mov_b64_e32 v[48:49], 0
	v_mov_b64_e32 v[50:51], 0
	v_mov_b64_e32 v[52:53], 0
	v_mov_b64_e32 v[54:55], 0
	v_mov_b64_e32 v[8:9], 0
	v_mov_b64_e32 v[10:11], 0
	v_mov_b64_e32 v[12:13], 0
	v_mov_b64_e32 v[14:15], 0
	v_mov_b64_e32 v[24:25], 0
	v_mov_b64_e32 v[26:27], 0
	v_mov_b64_e32 v[28:29], 0
	v_mov_b64_e32 v[30:31], 0
	v_mov_b64_e32 v[40:41], 0
	v_mov_b64_e32 v[42:43], 0
	v_mov_b64_e32 v[44:45], 0
	v_mov_b64_e32 v[46:47], 0
	v_mov_b64_e32 v[56:57], 0
	v_mov_b64_e32 v[58:59], 0
	v_mov_b64_e32 v[60:61], 0
	v_mov_b64_e32 v[62:63], 0
	v_mov_b64_e32 v[66:67], 0
	v_mov_b64_e32 v[68:69], 0
	v_mov_b64_e32 v[70:71], 0
	v_mov_b64_e32 v[72:73], 0
	v_mov_b64_e32 v[82:83], 0
	v_mov_b64_e32 v[84:85], 0
	v_mov_b64_e32 v[86:87], 0
	v_mov_b64_e32 v[88:89], 0
	v_mov_b64_e32 v[114:115], 0
	v_mov_b64_e32 v[116:117], 0
	v_mov_b64_e32 v[118:119], 0
	v_mov_b64_e32 v[120:121], 0
	v_mov_b64_e32 v[130:131], 0
	s_waitcnt vmcnt(0)
	v_mov_b64_e32 v[132:133], 0
	v_mov_b64_e32 v[134:135], 0
	v_mov_b64_e32 v[136:137], 0
	v_mov_b64_e32 v[74:75], 0
	v_mov_b64_e32 v[76:77], 0
	v_mov_b64_e32 v[78:79], 0
	v_mov_b64_e32 v[80:81], 0
	v_mov_b64_e32 v[90:91], 0
	v_mov_b64_e32 v[92:93], 0
	v_mov_b64_e32 v[94:95], 0
	v_mov_b64_e32 v[96:97], 0
	v_mov_b64_e32 v[122:123], 0
	v_mov_b64_e32 v[124:125], 0
	v_mov_b64_e32 v[126:127], 0
	v_mov_b64_e32 v[128:129], 0
	v_mov_b64_e32 v[138:139], 0
	v_mov_b64_e32 v[140:141], 0
	v_mov_b64_e32 v[142:143], 0
	v_mov_b64_e32 v[144:145], 0

.LBB0_1249:
	s_ashr_i32 s63, s62, 31
	s_lshl_b64 s[64:65], s[62:63], 19
	s_add_u32 s64, s34, s64
	s_addc_u32 s65, s35, s65
	s_and_b64 s[66:67], s[40:41], exec
	s_cselect_b32 s63, s65, s29
	s_cselect_b32 s70, s64, s28
	s_ashr_i32 s49, s48, 31
	s_lshl_b64 s[66:67], s[48:49], 19
	s_add_u32 s66, s47, s66
	s_addc_u32 s67, s61, s67
	s_and_b64 s[68:69], s[40:41], exec
	s_cselect_b32 s49, s67, s31
	s_cselect_b32 s71, s66, s30
	s_add_u32 s28, s28, 0x40080
	s_addc_u32 s29, s29, 0
	s_add_u32 s72, s30, 0x100
	v_mov_b32_e32 v0, 0
	s_addc_u32 s73, s31, 0
	s_mov_b32 s74, -2
	s_waitcnt lgkmcnt(0)
	v_mov_b32_e32 v1, v0
	v_mov_b64_e32 v[2:3], 0
	v_mov_b64_e32 v[4:5], 0
	v_mov_b64_e32 v[6:7], 0
	v_mov_b64_e32 v[8:9], 0
	v_mov_b64_e32 v[10:11], 0
	v_mov_b64_e32 v[12:13], 0
	v_mov_b64_e32 v[14:15], 0
	v_mov_b64_e32 v[16:17], 0
	v_mov_b64_e32 v[18:19], 0
	v_mov_b64_e32 v[20:21], 0
	v_mov_b64_e32 v[22:23], 0
	v_mov_b64_e32 v[24:25], 0
	v_mov_b64_e32 v[26:27], 0
	v_mov_b64_e32 v[28:29], 0
	v_mov_b64_e32 v[30:31], 0
	v_mov_b64_e32 v[66:67], 0
	s_waitcnt vmcnt(0)
	v_mov_b64_e32 v[68:69], 0
	v_mov_b64_e32 v[70:71], 0
	v_mov_b64_e32 v[72:73], 0
	v_mov_b64_e32 v[74:75], 0
	v_mov_b64_e32 v[76:77], 0
	v_mov_b64_e32 v[78:79], 0
	v_mov_b64_e32 v[80:81], 0
	v_mov_b64_e32 v[82:83], 0
	v_mov_b64_e32 v[84:85], 0
	v_mov_b64_e32 v[86:87], 0
	v_mov_b64_e32 v[88:89], 0
	v_mov_b64_e32 v[90:91], 0
	v_mov_b64_e32 v[92:93], 0
	v_mov_b64_e32 v[94:95], 0
	v_mov_b64_e32 v[96:97], 0
	v_mov_b64_e32 v[32:33], 0
	v_mov_b64_e32 v[34:35], 0
	v_mov_b64_e32 v[36:37], 0
	v_mov_b64_e32 v[38:39], 0
	v_mov_b64_e32 v[40:41], 0
	v_mov_b64_e32 v[42:43], 0
	v_mov_b64_e32 v[44:45], 0
	v_mov_b64_e32 v[46:47], 0
	v_mov_b64_e32 v[48:49], 0
	v_mov_b64_e32 v[50:51], 0
	v_mov_b64_e32 v[52:53], 0
	v_mov_b64_e32 v[54:55], 0
	v_mov_b64_e32 v[56:57], 0
	v_mov_b64_e32 v[58:59], 0
	v_mov_b64_e32 v[60:61], 0
	v_mov_b64_e32 v[62:63], 0
	v_mov_b64_e32 v[114:115], 0
	v_mov_b64_e32 v[116:117], 0
	v_mov_b64_e32 v[118:119], 0
	v_mov_b64_e32 v[120:121], 0
	v_mov_b64_e32 v[122:123], 0
	v_mov_b64_e32 v[124:125], 0
	v_mov_b64_e32 v[126:127], 0
	v_mov_b64_e32 v[128:129], 0
	v_mov_b64_e32 v[130:131], 0
	v_mov_b64_e32 v[132:133], 0
	v_mov_b64_e32 v[134:135], 0
	v_mov_b64_e32 v[136:137], 0
	v_mov_b64_e32 v[138:139], 0
	v_mov_b64_e32 v[140:141], 0
	v_mov_b64_e32 v[142:143], 0
	v_mov_b64_e32 v[144:145], 0

.LBB0_1383:
	s_ashr_i32 s49, s48, 31
	s_lshl_b64 s[62:63], s[48:49], 19
	s_add_u32 s62, s0, s62
	s_addc_u32 s63, s1, s63
	s_and_b64 s[64:65], s[38:39], exec
	s_cselect_b32 s49, s63, s31
	s_cselect_b32 s72, s62, s30
	s_ashr_i32 s45, s44, 31
	s_lshl_b64 s[64:65], s[44:45], 19
	s_add_u32 s64, s4, s64
	s_addc_u32 s65, s5, s65
	s_and_b64 s[70:71], s[38:39], exec
	s_cselect_b32 s45, s65, s69
	s_cselect_b32 s73, s64, s68
	s_add_u32 s30, s30, 0x40080
	s_addc_u32 s31, s31, 0
	s_add_u32 s74, s68, 0x100
	v_mov_b32_e32 v0, 0
	s_addc_u32 s75, s69, 0
	s_mov_b32 s76, -2
	v_mov_b32_e32 v1, v0
	v_mov_b64_e32 v[2:3], 0
	v_mov_b64_e32 v[4:5], 0
	v_mov_b64_e32 v[6:7], 0
	v_mov_b64_e32 v[16:17], 0
	v_mov_b64_e32 v[18:19], 0
	v_mov_b64_e32 v[20:21], 0
	v_mov_b64_e32 v[22:23], 0
	v_mov_b64_e32 v[32:33], 0
	v_mov_b64_e32 v[34:35], 0
	v_mov_b64_e32 v[36:37], 0
	v_mov_b64_e32 v[38:39], 0
	v_mov_b64_e32 v[48:49], 0
	v_mov_b64_e32 v[50:51], 0
	v_mov_b64_e32 v[52:53], 0
	v_mov_b64_e32 v[54:55], 0
	v_mov_b64_e32 v[8:9], 0
	v_mov_b64_e32 v[10:11], 0
	v_mov_b64_e32 v[12:13], 0
	v_mov_b64_e32 v[14:15], 0
	v_mov_b64_e32 v[24:25], 0
	v_mov_b64_e32 v[26:27], 0
	v_mov_b64_e32 v[28:29], 0
	v_mov_b64_e32 v[30:31], 0
	v_mov_b64_e32 v[40:41], 0
	v_mov_b64_e32 v[42:43], 0
	v_mov_b64_e32 v[44:45], 0
	v_mov_b64_e32 v[46:47], 0
	v_mov_b64_e32 v[56:57], 0
	v_mov_b64_e32 v[58:59], 0
	v_mov_b64_e32 v[60:61], 0
	v_mov_b64_e32 v[62:63], 0
	v_mov_b64_e32 v[66:67], 0
	v_mov_b64_e32 v[68:69], 0
	v_mov_b64_e32 v[70:71], 0
	v_mov_b64_e32 v[72:73], 0
	v_mov_b64_e32 v[82:83], 0
	v_mov_b64_e32 v[84:85], 0
	v_mov_b64_e32 v[86:87], 0
	v_mov_b64_e32 v[88:89], 0
	v_mov_b64_e32 v[98:99], 0
	v_mov_b64_e32 v[100:101], 0
	v_mov_b64_e32 v[102:103], 0
	v_mov_b64_e32 v[104:105], 0
	v_mov_b64_e32 v[130:131], 0
	s_waitcnt vmcnt(0)
	v_mov_b64_e32 v[132:133], 0
	v_mov_b64_e32 v[134:135], 0
	v_mov_b64_e32 v[136:137], 0
	v_mov_b64_e32 v[74:75], 0
	v_mov_b64_e32 v[76:77], 0
	v_mov_b64_e32 v[78:79], 0
	v_mov_b64_e32 v[80:81], 0
	v_mov_b64_e32 v[90:91], 0
	v_mov_b64_e32 v[92:93], 0
	v_mov_b64_e32 v[94:95], 0
	v_mov_b64_e32 v[96:97], 0
	v_mov_b64_e32 v[106:107], 0
	v_mov_b64_e32 v[108:109], 0
	v_mov_b64_e32 v[110:111], 0
	v_mov_b64_e32 v[112:113], 0
	v_mov_b64_e32 v[138:139], 0
	v_mov_b64_e32 v[140:141], 0
	v_mov_b64_e32 v[142:143], 0
	v_mov_b64_e32 v[144:145], 0

.LBB0_1460:
	s_ashr_i32 s71, s70, 31
	s_lshl_b64 s[48:49], s[70:71], 21
	s_add_u32 s72, s0, s48
	s_addc_u32 s73, s1, s49
	s_and_b64 s[48:49], s[44:45], exec
	s_cselect_b32 s35, s73, s29
	s_cselect_b32 s47, s72, s28
	s_ashr_i32 s69, s68, 31
	s_lshl_b64 s[48:49], s[68:69], 21
	s_add_u32 s74, s4, s48
	s_addc_u32 s75, s5, s49
	s_and_b64 s[48:49], s[44:45], exec
	s_cselect_b32 s69, s75, s31
	s_cselect_b32 s71, s74, s30
	s_add_u32 s28, s28, 0x100080
	s_addc_u32 s29, s29, 0
	s_add_u32 s82, s30, 0x100
	v_mov_b32_e32 v0, 0
	s_addc_u32 s83, s31, 0
	s_mov_b32 s91, -2
	v_mov_b32_e32 v1, v0
	v_mov_b64_e32 v[2:3], 0
	v_mov_b64_e32 v[4:5], 0
	v_mov_b64_e32 v[6:7], 0
	v_mov_b64_e32 v[16:17], 0
	v_mov_b64_e32 v[18:19], 0
	v_mov_b64_e32 v[20:21], 0
	v_mov_b64_e32 v[22:23], 0
	v_mov_b64_e32 v[32:33], 0
	v_mov_b64_e32 v[34:35], 0
	v_mov_b64_e32 v[36:37], 0
	v_mov_b64_e32 v[38:39], 0
	v_mov_b64_e32 v[48:49], 0
	v_mov_b64_e32 v[50:51], 0
	v_mov_b64_e32 v[52:53], 0
	v_mov_b64_e32 v[54:55], 0
	v_mov_b64_e32 v[8:9], 0
	v_mov_b64_e32 v[10:11], 0
	v_mov_b64_e32 v[12:13], 0
	v_mov_b64_e32 v[14:15], 0
	v_mov_b64_e32 v[24:25], 0
	v_mov_b64_e32 v[26:27], 0
	v_mov_b64_e32 v[28:29], 0
	v_mov_b64_e32 v[30:31], 0
	v_mov_b64_e32 v[40:41], 0
	v_mov_b64_e32 v[42:43], 0
	v_mov_b64_e32 v[44:45], 0
	v_mov_b64_e32 v[46:47], 0
	v_mov_b64_e32 v[56:57], 0
	v_mov_b64_e32 v[58:59], 0
	v_mov_b64_e32 v[60:61], 0
	v_mov_b64_e32 v[62:63], 0
	v_mov_b64_e32 v[66:67], 0
	s_waitcnt vmcnt(0)
	v_mov_b64_e32 v[68:69], 0
	v_mov_b64_e32 v[70:71], 0
	v_mov_b64_e32 v[72:73], 0
	v_mov_b64_e32 v[82:83], 0
	v_mov_b64_e32 v[84:85], 0
	v_mov_b64_e32 v[86:87], 0
	v_mov_b64_e32 v[88:89], 0
	v_mov_b64_e32 v[98:99], 0
	v_mov_b64_e32 v[100:101], 0
	v_mov_b64_e32 v[102:103], 0
	v_mov_b64_e32 v[104:105], 0
	v_mov_b64_e32 v[134:135], 0
	v_mov_b64_e32 v[136:137], 0
	v_mov_b64_e32 v[142:143], 0
	v_mov_b64_e32 v[144:145], 0
	v_mov_b64_e32 v[74:75], 0
	v_mov_b64_e32 v[76:77], 0
	v_mov_b64_e32 v[78:79], 0
	v_mov_b64_e32 v[80:81], 0
	v_mov_b64_e32 v[90:91], 0
	v_mov_b64_e32 v[92:93], 0
	v_mov_b64_e32 v[94:95], 0
	v_mov_b64_e32 v[96:97], 0
	v_mov_b64_e32 v[106:107], 0
	v_mov_b64_e32 v[108:109], 0
	v_mov_b64_e32 v[110:111], 0
	v_mov_b64_e32 v[112:113], 0
	v_mov_b64_e32 v[122:123], 0
	v_mov_b64_e32 v[124:125], 0
	v_mov_b64_e32 v[126:127], 0
	v_mov_b64_e32 v[128:129], 0

.LBB0_1531:
	s_ashr_i32 s49, s48, 31
	s_lshl_b64 s[62:63], s[48:49], 21
	s_add_u32 s62, s5, s62
	s_addc_u32 s63, s34, s63
	s_and_b64 s[64:65], s[40:41], exec
	s_cselect_b32 s49, s63, s29
	s_cselect_b32 s68, s62, s28
	s_ashr_i32 s47, s46, 31
	s_lshl_b64 s[64:65], s[46:47], 21
	s_add_u32 s64, s35, s64
	s_addc_u32 s65, s61, s65
	s_and_b64 s[66:67], s[40:41], exec
	s_cselect_b32 s47, s65, s31
	s_cselect_b32 s69, s64, s30
	s_add_u32 s28, s28, 0x100080
	s_addc_u32 s29, s29, 0
	s_add_u32 s70, s30, 0x100
	v_mov_b32_e32 v0, 0
	s_addc_u32 s71, s31, 0
	s_mov_b32 s72, -2
	s_waitcnt lgkmcnt(0)
	v_mov_b32_e32 v1, v0
	v_mov_b64_e32 v[2:3], 0
	v_mov_b64_e32 v[4:5], 0
	v_mov_b64_e32 v[6:7], 0
	v_mov_b64_e32 v[8:9], 0
	v_mov_b64_e32 v[10:11], 0
	v_mov_b64_e32 v[12:13], 0
	v_mov_b64_e32 v[14:15], 0
	v_mov_b64_e32 v[16:17], 0
	v_mov_b64_e32 v[18:19], 0
	v_mov_b64_e32 v[20:21], 0
	v_mov_b64_e32 v[22:23], 0
	v_mov_b64_e32 v[24:25], 0
	v_mov_b64_e32 v[26:27], 0
	v_mov_b64_e32 v[28:29], 0
	v_mov_b64_e32 v[30:31], 0
	v_mov_b64_e32 v[66:67], 0
	s_waitcnt vmcnt(0)
	v_mov_b64_e32 v[68:69], 0
	v_mov_b64_e32 v[70:71], 0
	v_mov_b64_e32 v[72:73], 0
	v_mov_b64_e32 v[74:75], 0
	v_mov_b64_e32 v[76:77], 0
	v_mov_b64_e32 v[78:79], 0
	v_mov_b64_e32 v[80:81], 0
	v_mov_b64_e32 v[82:83], 0
	v_mov_b64_e32 v[84:85], 0
	v_mov_b64_e32 v[86:87], 0
	v_mov_b64_e32 v[88:89], 0
	v_mov_b64_e32 v[90:91], 0
	v_mov_b64_e32 v[92:93], 0
	v_mov_b64_e32 v[94:95], 0
	v_mov_b64_e32 v[96:97], 0
	v_mov_b64_e32 v[32:33], 0
	v_mov_b64_e32 v[34:35], 0
	v_mov_b64_e32 v[36:37], 0
	v_mov_b64_e32 v[38:39], 0
	v_mov_b64_e32 v[40:41], 0
	v_mov_b64_e32 v[42:43], 0
	v_mov_b64_e32 v[44:45], 0
	v_mov_b64_e32 v[46:47], 0
	v_mov_b64_e32 v[48:49], 0
	v_mov_b64_e32 v[50:51], 0
	v_mov_b64_e32 v[52:53], 0
	v_mov_b64_e32 v[54:55], 0
	v_mov_b64_e32 v[56:57], 0
	v_mov_b64_e32 v[58:59], 0
	v_mov_b64_e32 v[60:61], 0
	v_mov_b64_e32 v[62:63], 0
	v_mov_b64_e32 v[114:115], 0
	v_mov_b64_e32 v[116:117], 0
	v_mov_b64_e32 v[118:119], 0
	v_mov_b64_e32 v[120:121], 0
	v_mov_b64_e32 v[122:123], 0
	v_mov_b64_e32 v[124:125], 0
	v_mov_b64_e32 v[126:127], 0
	v_mov_b64_e32 v[128:129], 0
	v_mov_b64_e32 v[130:131], 0
	v_mov_b64_e32 v[132:133], 0
	v_mov_b64_e32 v[134:135], 0
	v_mov_b64_e32 v[136:137], 0
	v_mov_b64_e32 v[138:139], 0
	v_mov_b64_e32 v[140:141], 0
	v_mov_b64_e32 v[142:143], 0
	v_mov_b64_e32 v[144:145], 0
